# v53 + w_out GEMM gets the same transposed latent tile order (4 panels x 8 column tiles per XCD per round)
# baseline (speedup 1.0000x reference)
;     __device__ __forceinline__ unsigned code(int i, unsigned& ko_) const { Unit u; u.pm = 0; u.pn = 0; u.ko = 0; u.nk = 0; u.ks = 0; const bool ok = next(i, u); ko_ = (unsigned)u.ko; return ok ? (0x80000000u | ((unsigned)u.nk << 16) | ((unsigned)u.pm << 8) | (unsigned)u.pn) : 0u; }
;     __host__ __device__ __forceinline__ bool next(int i, Unit& u) const {
;         const long L = (long)i * G + c; if (L >= nwg) return false;
;         int wgid = (int)L; { const int q = nwg / NXCD, r = nwg % NXCD, xcd = wgid % NXCD, off = wgid / NXCD; wgid = (xcd < r ? xcd * (q + 1) : r * (q + 1) + (xcd - r) * q) + off; }
;         const int nig = WGM * nN, gid = wgid / nig, fm = gid * WGM, gsz = (nM - fm) < WGM ? (nM - fm) : WGM;
;         u.pm = fm + ((wgid % nig) % gsz); u.pn = (wgid % nig) / gsz; u.ko = 0; u.nk = nk; return true;
;     }
;         const int pair = (K / 64) / (nks_ / 2); t1 = ((pair / 2 + 1) / 2) * 2; t2 = pair - t1; }
;     __device__ __forceinline__ unsigned code(int i, unsigned& ko_) const {
;         const int L = i * lat.G + lat.c; if (L < nlat) return lat.code(i, ko_);
;         const int Lp = L - nlat; if (Lp >= nsp) { ko_ = 0u; return 0u; }
;         const int r = Lp / nks, ks = Lp % nks; ko_ = (unsigned)(((ks >> 1) * (t1 + t2) + (ks & 1) * t1) * 64);
;         return 0x80000000u | ((unsigned)ks << 24) | ((unsigned)((ks & 1) ? t2 : t1) << 16) | ((unsigned)(64 + (r & 3)) << 8) | (unsigned)(r >> 2);
;     }
.LBB0_250:
	s_or_b64 exec, exec, s[36:37]
	s_cmpk_lt_i32 s92, 0xbb0
	s_cselect_b64 s[0:1], -1, 0
	v_writelane_b32 v254, s0, 6
	s_ashr_i32 s90, s92, 31
	s_bfe_u32 s2, s92, 0x20001
	v_writelane_b32 v254, s1, 7
	s_lshr_b32 s0, s90, 29
	s_and_b32 s3, s92, 1
	s_add_i32 s0, s92, s0
	s_mul_i32 s2, s2, 22
	s_mul_i32 s4, s3, 12
	s_ashr_i32 s17, s0, 3
	s_and_b32 s0, s0, -8
	s_and_b32 s1, s92, 7
	s_add_i32 s2, s2, s4
	s_sub_i32 s18, s92, s0
	s_and_b32 s0, s92, 0x7fffff00
	s_lshl_b32 s2, s2, 6
	s_lshl_b32 s1, s1, 24
	s_cmp_eq_u32 s3, 0
	s_mov_b32 s3, 0xc0000
	s_cselect_b32 s3, s3, 0xa0000
	s_lshl_b32 s4, s92, 5
	s_and_b32 s4, s4, 0x300
	s_bfe_u32 s5, s92, 0x30005
	s_or_b32 s4, s5, s4
	s_or_b32 s1, s4, s1
	s_or_b32 s3, s1, s3
	s_or_b32 s3, s3, 0x80004000
	s_lshl_b32 s4, s18, 6
	s_lshl_b32 s6, s92, 9
	s_lshl_b32 s5, s92, 2
	s_cmpk_lt_i32 s5, 0x400
	v_writelane_b32 v254, s5, 8
	s_cselect_b64 s[8:9], -1, 0
	v_writelane_b32 v254, s8, 9
	s_lshl_b32 s7, s92, 24
	s_and_b32 s7, s7, 0x3000000
	v_writelane_b32 v254, s9, 10
	s_lshl_b32 s8, s92, 6
	s_bfe_u32 s10, s92, 0x40004
	s_and_b32 s9, s8, 0x300
	s_or_b32 s7, s7, s10
	s_or_b32 s7, s7, s9
	s_add_i32 s5, s92, 0xfffffd00
	v_writelane_b32 v254, s6, 11
	s_and_b32 s6, s6, 0x600
	s_or_b32 s7, s7, 0x80084000
	s_cmpk_lt_i32 s92, 0xcc
	s_cselect_b64 s[10:11], -1, 0
	s_lshl_b32 s12, s94, 8
	s_add_i32 s59, s12, 0
	s_lshl_b32 s12, s94, 12
	v_writelane_b32 v254, s10, 12
	s_add_i32 s12, s12, 0
	s_add_i32 s12, s12, 0x14800
	v_writelane_b32 v254, s11, 13
	v_writelane_b32 v254, s12, 14
	s_add_i32 s12, s92, 0xfffffe00
	s_mul_i32 s9, s18, 25
	v_writelane_b32 v254, s12, 15
	s_lshl_b32 s12, s92, 8
	s_add_i32 s9, s9, 4
	s_add_i32 s10, s92, 0xcc
	s_add_i32 s11, s92, 0xdc
	s_add_i32 s95, s59, 0x10000
	s_lshl_b32 s19, s94, 5
	s_add_i32 s59, s59, 0x14000
	s_and_b32 s12, s12, 0x700
	s_or_b32 s1, s1, 0x80044000
	v_writelane_b32 v254, s12, 16
	s_cmp_lt_i32 s18, 0
	s_movk_i32 s12, 0x177
	v_writelane_b32 v254, s1, 17
	s_mul_i32 s1, s18, 0x41
	s_cselect_b32 s12, s12, 0x176
	s_mul_i32 s12, s18, s12
	s_cselect_b32 s1, s1, s4
	s_movk_i32 s4, 0x61
	s_cselect_b32 s4, s4, 0x60
	s_add_i32 s12, s12, s17
	s_mul_hi_i32 s13, s12, 0x2e8ba2e9
	s_lshr_b32 s14, s13, 31
	s_ashr_i32 s13, s13, 6
	s_add_i32 s13, s13, s14
	s_mul_i32 s14, s13, 0x160
	s_lshl_b32 s13, s13, 3
	s_sub_i32 s15, 0x44, s13
	s_min_u32 s15, s15, 8
	s_sub_i32 s12, s12, s14
	s_cmpk_eq_i32 s0, 0x200
	s_cselect_b32 s2, s2, 0
	s_cselect_b32 s3, s3, 0
	s_add_i32 s0, s1, s17
	s_ashr_i32 s1, s0, 31
	s_lshr_b32 s1, s1, 26
	s_add_i32 s1, s0, s1
	s_and_b32 s14, s1, 0xffc0
	s_sub_i32 s0, s0, s14
	s_bfe_i32 s14, s0, 0x80000
	s_bfe_u32 s14, s14, 0x3000c
	s_add_i32 s14, s0, s14
	s_bfe_i32 s16, s14, 0x80000
	s_and_b32 s14, s14, 0xf8
	s_sub_i32 s0, s0, s14
	s_sext_i32_i8 s0, s0
	s_lshl_b32 s1, s1, 5
	s_sext_i32_i16 s16, s16
	s_and_b32 s1, s1, 0xfffff800
	s_lshl_b32 s0, s0, 8
	s_ashr_i32 s14, s16, 3
	s_add_i32 s0, s0, s1
	s_or_b32 s0, s0, s14
	s_or_b32 s14, s0, 0x80580000
	s_cmpk_lt_u32 s5, 0xc0
	s_mul_i32 s4, s18, s4
	s_cselect_b32 s1, s6, 0
	s_cselect_b32 s5, s7, 0
	s_add_i32 s4, s4, s17
	s_mul_hi_i32 s6, s4, 0x2aaaaaab
	s_lshr_b32 s7, s6, 31
	s_ashr_i32 s6, s6, 4
	s_add_i32 s6, s6, s7
	s_mul_i32 s7, s6, 0x60
	s_sub_i32 s4, s4, s7
	s_bfe_i32 s7, s4, 0x80000
	s_bfe_u32 s7, s7, 0x3000c
	s_add_i32 s7, s4, s7
	s_bfe_i32 s16, s7, 0x80000
	s_and_b32 s7, s7, 0xf8
	s_sub_i32 s4, s4, s7
	s_sext_i32_i8 s4, s4
	s_sext_i32_i16 s16, s16
	s_lshl_b32 s6, s6, 11
	s_lshl_b32 s4, s4, 8
	s_ashr_i32 s7, s16, 3
	s_add_i32 s4, s4, s6
	s_or_b32 s4, s4, s7
	s_or_b32 s4, s4, 0x80200000
	s_cmp_lt_i32 s18, 4
	s_mul_i32 s6, s18, 26
	s_cselect_b32 s6, s6, s9
	s_add_i32 s6, s6, s17
	s_mul_hi_i32 s7, s6, 0x2aaaaaab
	s_lshr_b32 s9, s7, 31
	s_ashr_i32 s7, s7, 2
	s_add_i32 s7, s7, s9
	s_lshl_b32 s9, s7, 3
;     __host__ __device__ __forceinline__ bool next(int i, Unit& u) const {
;         const long L = (long)i * G + c; if (L >= nwg) return false;
;         int wgid = (int)L; { const int q = nwg / NXCD, r = nwg % NXCD, xcd = wgid % NXCD, off = wgid / NXCD; wgid = (xcd < r ? xcd * (q + 1) : r * (q + 1) + (xcd - r) * q) + off; }
;         const int nig = WGM * nN, gid = wgid / nig, fm = gid * WGM, gsz = (nM - fm) < WGM ? (nM - fm) : WGM;
;         u.pm = fm + ((wgid % nig) % gsz); u.pn = (wgid % nig) / gsz; u.ko = 0; u.nk = nk; return true;
;     }
	s_sub_i32 s16, 0x44, s9
	s_mul_i32 s7, s7, 24
	s_min_u32 s16, s16, 8
	s_sub_i32 s6, s6, s7
	s_or_b32 s0, s0, 0x80200000
	v_writelane_b32 v254, s17, 18
	s_cmpk_lt_i32 s92, 0x300
	v_writelane_b32 v254, s0, 19
	s_cselect_b32 s0, 0, s1
	v_writelane_b32 v254, s0, 20
	v_cvt_f32_ubyte0_e32 v1, s15
	v_cvt_f32_i32_e32 v0, s12
	v_writelane_b32 v254, s1, 21
	s_cselect_b32 s0, s4, s5
	v_writelane_b32 v254, s0, 22
	v_writelane_b32 v254, s18, 23
	s_lshr_b32 s0, s18, 31
	v_writelane_b32 v254, s0, 24
	s_mul_i32 s4, s94, 0x21000
	v_writelane_b32 v254, s4, 25
	s_cmpk_lt_i32 s92, 0x200
	v_writelane_b32 v254, s19, 26
	s_mul_hi_u32 s4, s19, 0x1080
	s_cselect_b64 s[0:1], -1, 0
	v_writelane_b32 v254, s4, 27
	v_rcp_iflag_f32_e32 v2, v1
	v_writelane_b32 v254, s0, 28
	s_mov_b64 s[4:5], -1
	s_movk_i32 s73, 0x600
	v_writelane_b32 v254, s1, 29
	s_and_b64 s[0:1], s[0:1], exec
	s_cselect_b32 s0, 0, s2
	v_writelane_b32 v254, s0, 30
	v_mul_f32_e32 v2, v0, v2
	v_trunc_f32_e32 v2, v2
	v_writelane_b32 v254, s1, 31
	s_cselect_b32 s0, s14, s3
	v_writelane_b32 v254, s0, 32
	s_cselect_b32 s0, s14, 0
	v_fma_f32 v0, -v2, v1, v0
	v_cvt_i32_f32_e32 v2, v2
	v_writelane_b32 v254, s0, 33
	s_and_b32 s0, s92, 7
	s_lshl_b32 s0, s0, 3
	s_lshr_b32 s1, s92, 6
	s_add_i32 s0, s0, s1
	s_lshl_b32 s0, s0, 8
	s_bfe_u32 s1, s92, 0x30003
	s_or_b32 s0, s0, s1
	s_or_b32 s1, s0, 0x80200000
	s_or_b32 s0, s0, 0x80580000
	v_writelane_b32 v254, s1, 19
	v_writelane_b32 v254, s0, 32
	v_writelane_b32 v254, s0, 33
	s_ashr_i32 s0, s12, 30
	s_or_b32 s2, s0, 1
	v_cmp_ge_f32_e64 s[0:1], |v0|, v1
	s_and_b64 s[0:1], s[0:1], exec
	s_cselect_b32 s0, s2, 0
	v_readfirstlane_b32 s1, v2
	s_add_i32 s0, s1, s0
	v_cvt_f32_ubyte0_e32 v1, s16
	s_sext_i32_i16 s1, s0
	s_mul_i32 s0, s0, s15
	v_cvt_f32_i32_e32 v0, s6
	v_rcp_iflag_f32_e32 v2, v1
	s_sub_i32 s0, s12, s0
	s_sext_i32_i16 s0, s0
	s_add_i32 s13, s13, s0
	s_lshl_b32 s0, s13, 8
	v_mul_f32_e32 v2, v0, v2
	s_or_b32 s0, s0, s1
	v_trunc_f32_e32 v2, v2
	s_or_b32 s0, s0, 0x80200000
	v_fma_f32 v0, -v2, v1, v0
	v_cvt_i32_f32_e32 v2, v2
	v_writelane_b32 v254, s0, 34
	s_ashr_i32 s0, s6, 30
	s_or_b32 s2, s0, 1
	v_cmp_ge_f32_e64 s[0:1], |v0|, v1
	s_and_b64 s[0:1], s[0:1], exec
	s_cselect_b32 s0, s2, 0
	v_readfirstlane_b32 s1, v2
	s_add_i32 s0, s1, s0
	s_sext_i32_i8 s1, s0
	s_mul_i32 s0, s0, s16
	s_sub_i32 s0, s6, s0
	s_sext_i32_i8 s0, s0
	s_add_i32 s9, s9, s0
	s_lshl_b32 s0, s9, 8
	s_or_b32 s0, s0, s1
	s_or_b32 s0, s0, 0x80080000
	v_writelane_b32 v254, s0, 35
	s_ashr_i32 s0, s10, 31
	v_writelane_b32 v254, s0, 36
	s_abs_i32 s0, s10
	v_writelane_b32 v254, s0, 37
	s_ashr_i32 s0, s11, 31
	v_writelane_b32 v254, s0, 38
	s_abs_i32 s0, s11
	v_writelane_b32 v254, s0, 39
	s_or_b32 s0, s8, 7
	v_writelane_b32 v254, s0, 40
	s_add_i32 s0, 0, 0x25ff0
	v_writelane_b32 v254, s0, 41
	s_add_i32 s0, 0, 0x25ff4
	v_writelane_b32 v254, s0, 42
	s_mov_b32 s2, 0
	v_writelane_b32 v254, s2, 43
	v_writelane_b32 v254, s4, 45
	s_movk_i32 s3, 0x1800
	s_mov_b32 s2, s92
	v_writelane_b32 v254, s5, 46
	v_writelane_b32 v254, s96, 47
	s_movk_i32 s66, 0x1080
	v_mov_b32_e32 v193, 0
	v_writelane_b32 v254, s97, 48
	v_writelane_b32 v254, s2, 49
	v_mov_b32_e32 v243, 1
	v_mov_b32_e32 v241, 0x358637bd
	v_writelane_b32 v254, s3, 50
	v_writelane_b32 v254, s94, 51
	s_mov_b32 s68, 0x800000
	s_mov_b32 s79, 0xc00000
	s_movk_i32 s91, 0x1000
	s_mov_b32 s1, 0x42b504f3
	s_mov_b32 s0, 0x1c8ff000
	s_mov_b32 s67, 0x1c07f000
	s_mov_b32 s61, 0x1c907000
	s_mov_b32 s64, 0x1c087000
	s_mov_b32 s69, 0x42ddb3d8
	s_mov_b32 s38, 0x2048f000
	s_mov_b32 s39, 0x1eb1f000
	s_mov_b32 s63, 0x2049f000
	s_mov_b32 s82, 0x1eb37000
	s_mov_b64 s[74:75], 0x20000
	s_mov_b32 s76, 0x3e0293ee
	s_mov_b32 s78, 0x3dd53b94
	s_mov_b64 s[80:81], 0x30000
	s_mov_b32 s41, 0
	v_writelane_b32 v254, s90, 52
	s_waitcnt lgkmcnt(0)
	s_barrier
	s_branch .LBB0_254

;     __host__ __device__ __forceinline__ bool next(int i, Unit& u) const {
;     ...
;         int wgid = (int)L; { const int q = nwg / NXCD, r = nwg % NXCD, xcd = wgid % NXCD, off = wgid / NXCD; wgid = (xcd < r ? xcd * (q + 1) : r * (q + 1) + (xcd - r) * q) + off; }
;         const int nig = WGM * nN, gid = wgid / nig, fm = gid * WGM, gsz = (nM - fm) < WGM ? (nM - fm) : WGM;
;         u.pm = fm + ((wgid % nig) % gsz); u.pn = (wgid % nig) / gsz; u.ko = 0; u.nk = nk; return true;
.LBB0_1025:
	s_ashr_i32 s9, s9, 3
	s_add_i32 s9, s12, s9
	s_ashr_i32 s11, s9, 31
	s_lshr_b32 s11, s11, 26
	s_add_i32 s11, s9, s11
	s_ashr_i32 s12, s11, 6
	s_lshl_b32 s12, s12, 3
	s_sub_i32 s13, 64, s12
	s_min_i32 s13, s13, 8
	s_abs_i32 s26, s13
	v_cvt_f32_u32_e32 v0, s26
	s_sub_i32 s28, 0, s26
	s_andn2_b32 s11, s11, 63
	s_sub_i32 s9, s9, s11
	v_rcp_iflag_f32_e32 v0, v0
	s_abs_i32 s11, s9
	s_xor_b32 s27, s9, s13
	s_ashr_i32 s27, s27, 31
	v_mul_f32_e32 v0, 0x4f7ffffe, v0
	v_cvt_u32_f32_e32 v0, v0
	s_nop 0
	v_readfirstlane_b32 s29, v0
	s_mul_i32 s28, s28, s29
	s_mul_hi_u32 s28, s29, s28
	s_add_i32 s29, s29, s28
	s_mul_hi_u32 s28, s11, s29
	s_mul_i32 s29, s28, s26
	s_sub_i32 s11, s11, s29
	s_add_i32 s33, s28, 1
	s_sub_i32 s29, s11, s26
	s_cmp_ge_u32 s11, s26
	s_cselect_b32 s28, s33, s28
	s_cselect_b32 s11, s29, s11
	s_add_i32 s29, s28, 1
	s_cmp_ge_u32 s11, s26
	s_cselect_b32 s11, s29, s28
	s_xor_b32 s11, s11, s27
	s_sub_i32 s11, s11, s27
	s_mul_i32 s13, s11, s13
	s_sub_i32 s9, s9, s13
	s_add_i32 s12, s12, s11
	s_lshl_b32 s12, s12, 8
	s_or_b32 s9, s9, s12
	s_or_b32 s9, s9, 0x80200000
